# sample-row GEMM (s4/s6): 3 K-steps of global prefetch in flight instead of 1
# baseline (speedup 1.0000x reference)
.LBB0_227:
	v_mov_b32_e32 v35, v142
	s_lshl_b32 s1, s15, 2
	s_andn2_b32 s1, s1, 63
	v_ashrrev_i32_e32 v34, 3, v35
	v_lshlrev_b32_e32 v0, 3, v35
	v_and_b32_e32 v6, 56, v0
	v_add_u32_e32 v0, s1, v34
	s_waitcnt lgkmcnt(0)
	v_mad_u64_u32 v[2:3], s[8:9], v0, s18, 0
	s_waitcnt lgkmcnt(0)
	v_ashrrev_i32_e32 v4, 31, v0
	v_mov_b32_e32 v0, v3
	v_mad_u64_u32 v[4:5], s[8:9], v4, s18, v[0:1]
	s_lshl_b32 s0, s15, 6
	v_mov_b32_e32 v3, v4
	s_and_b32 s0, s0, 0x3c0
	v_lshl_add_u64 v[2:3], v[2:3], 1, s[2:3]
	v_lshlrev_b32_e32 v28, 1, v6
	v_mov_b32_e32 v29, v1
	v_add_u32_e32 v0, s0, v34
	v_lshl_add_u64 v[18:19], v[2:3], 0, v[28:29]
	v_mad_u64_u32 v[2:3], s[8:9], v0, s18, 0
	v_ashrrev_i32_e32 v4, 31, v0
	v_mov_b32_e32 v0, v3
	v_mad_u64_u32 v[4:5], s[8:9], v4, s18, v[0:1]
	v_mov_b32_e32 v3, v4
	v_lshl_add_u64 v[2:3], v[2:3], 1, s[16:17]
	v_lshl_add_u64 v[20:21], v[2:3], 0, v[28:29]
	global_load_dwordx4 v[2:5], v[18:19], off
	global_load_dwordx4 v[6:9], v[18:19], off offset:128
	global_load_dwordx4 v[10:13], v[20:21], off
	global_load_dwordx4 v[14:17], v[20:21], off offset:128
	s_movk_i32 s8, 0x88
	v_mul_lo_u32 v0, v34, s8
	v_lshlrev_b32_e32 v42, 1, v0
	v_add3_u32 v0, s89, v42, v28
	s_waitcnt lgkmcnt(0)
	s_barrier
	v_bfe_u32 v29, v35, 4, 2
	v_lshl_add_u32 v22, v29, 4, s89
	v_and_b32_e32 v26, 0xffffffe0, v34
	s_addk_i32 s1, 0x4000
	s_and_b32 s48, s5, 0x3c0
	s_and_b32 s28, s14, 0xffffffc0
	s_ashr_i32 s29, s28, 31
	v_lshlrev_b32_e32 v45, 3, v29
	s_waitcnt vmcnt(3)
	ds_write_b128 v0, v[2:5]
	s_waitcnt vmcnt(2)
	ds_write_b128 v0, v[6:9] offset:128
	s_waitcnt vmcnt(1)
	ds_write_b128 v0, v[10:13] offset:34816
	s_waitcnt vmcnt(0)
	ds_write_b128 v0, v[14:17] offset:34944
	s_waitcnt lgkmcnt(0)
	s_barrier
	v_mov_b64_e32 v[92:93], v[18:19]
	v_mov_b64_e32 v[94:95], v[20:21]
	global_load_dwordx4 v[6:9], v[18:19], off offset:256
	global_load_dwordx4 v[10:13], v[18:19], off offset:384
	global_load_dwordx4 v[14:17], v[20:21], off offset:256
	s_nop 0
	global_load_dwordx4 v[18:21], v[20:21], off offset:384
	global_load_dwordx4 v[60:63], v[92:93], off offset:512
	global_load_dwordx4 v[64:67], v[92:93], off offset:640
	global_load_dwordx4 v[68:71], v[94:95], off offset:512
	global_load_dwordx4 v[72:75], v[94:95], off offset:640
	global_load_dwordx4 v[76:79], v[92:93], off offset:768
	global_load_dwordx4 v[80:83], v[92:93], off offset:896
	global_load_dwordx4 v[84:87], v[94:95], off offset:768
	global_load_dwordx4 v[88:91], v[94:95], off offset:896
	s_mov_b32 s98, 0
	v_lshrrev_b32_e32 v2, 2, v35
	v_and_b32_e32 v0, 15, v35
	v_and_b32_e32 v37, 48, v2
	v_or_b32_e32 v2, v37, v0
	v_mul_u32_u24_e32 v43, 0x88, v2
	v_lshl_add_u32 v27, v43, 1, v22
	ds_read_b128 v[2:5], v27 offset:34816
	v_or_b32_e32 v23, v26, v0
	v_mul_lo_u32 v44, v23, s8
	v_lshl_add_u32 v36, v44, 1, v22
	ds_read_b128 v[22:25], v36
	ds_read_b128 v[30:33], v36 offset:4352
	ds_read_b128 v[38:41], v27 offset:34880
	s_waitcnt lgkmcnt(2)
	v_mfma_f32_16x16x32_bf16 v[22:25], v[2:5], v[22:25], 0
	v_or_b32_e32 v0, s1, v0
	v_add_u32_e32 v26, v0, v26
	v_and_b32_e32 v0, 7, v35
	s_waitcnt lgkmcnt(1)
	v_mfma_f32_16x16x32_bf16 v[2:5], v[2:5], v[30:33], 0
	ds_read_b128 v[30:33], v36 offset:64
	v_ashrrev_i32_e32 v35, 31, v34
	s_mov_b32 s8, 1
	s_waitcnt lgkmcnt(0)
	v_mfma_f32_16x16x32_bf16 v[22:25], v[38:41], v[30:33], v[22:25]
	ds_read_b128 v[30:33], v36 offset:4416
	ds_read_b128 v[46:49], v27 offset:34944
	ds_read_b128 v[50:53], v36 offset:128
	v_lshlrev_b32_e32 v0, 4, v0
	s_waitcnt lgkmcnt(2)
	v_mfma_f32_16x16x32_bf16 v[2:5], v[38:41], v[30:33], v[2:5]
	ds_read_b128 v[30:33], v36 offset:4480
	ds_read_b128 v[38:41], v27 offset:35008
	v_ashrrev_i32_e32 v27, 31, v26
	s_mov_b32 s1, 64
	s_waitcnt lgkmcnt(2)
	v_mfma_f32_16x16x32_bf16 v[22:25], v[46:49], v[50:53], v[22:25]
	ds_read_b128 v[50:53], v36 offset:192
	s_waitcnt lgkmcnt(2)
	v_mfma_f32_16x16x32_bf16 v[2:5], v[46:49], v[30:33], v[2:5]
	ds_read_b128 v[30:33], v36 offset:4544
	v_mov_b64_e32 v[46:47], s[16:17]
	s_waitcnt lgkmcnt(0)
	v_mfma_f32_16x16x32_bf16 v[2:5], v[38:41], v[30:33], v[2:5]
	v_lshl_add_u64 v[32:33], s[48:49], 0, v[34:35]
	v_mul_lo_u32 v36, s12, v33
	v_lshl_add_u64 v[34:35], v[34:35], 0, s[28:29]
	v_mfma_f32_16x16x32_bf16 v[22:25], v[38:41], v[50:53], v[22:25]
	v_mul_lo_u32 v38, s13, v32
	v_mad_u64_u32 v[32:33], s[30:31], s12, v32, v[46:47]
	v_add3_u32 v33, v38, v33, v36
	v_mov_b64_e32 v[38:39], 0x8000
	v_lshl_add_u64 v[38:39], v[34:35], 1, v[38:39]
	v_mov_b64_e32 v[34:35], s[20:21]
	v_mad_u64_u32 v[34:35], s[28:29], s18, v38, v[34:35]
	v_mov_b32_e32 v36, v35
	v_mad_u64_u32 v[38:39], s[28:29], s18, v39, v[36:37]
	v_lshl_add_u64 v[30:31], v[26:27], 3, s[24:25]
	v_mov_b32_e32 v35, v38
.LBB0_228:
	s_and_b32 s9, s1, 64
	s_mulk_i32 s9, 0x110
	s_add_i32 s23, s89, s9
	v_add3_u32 v36, s23, v42, v28
	s_add_i32 s99, s8, 2
	s_cmp_lt_u32 s99, s4
	s_cbranch_scc0 .Lsgb_wt
	s_waitcnt vmcnt(8)
	s_branch .Lsgb_wd

.Lsgb_wd:
	s_cmp_eq_u32 s98, 1
	s_cbranch_scc1 .Lsgb_w1
	s_cmp_eq_u32 s98, 2
	s_cbranch_scc1 .Lsgb_w2
	ds_write_b128 v36, v[6:9]
	ds_write_b128 v36, v[10:13] offset:128
	ds_write_b128 v36, v[14:17] offset:34816
	ds_write_b128 v36, v[18:21] offset:34944
	s_branch .Lsgb_we
.Lsgb_w1:
	ds_write_b128 v36, v[60:63]
	ds_write_b128 v36, v[64:67] offset:128
	ds_write_b128 v36, v[68:71] offset:34816
	ds_write_b128 v36, v[72:75] offset:34944
	s_branch .Lsgb_we
.Lsgb_w2:
	ds_write_b128 v36, v[76:79]
	ds_write_b128 v36, v[80:83] offset:128
	ds_write_b128 v36, v[84:87] offset:34816
	ds_write_b128 v36, v[88:91] offset:34944
.Lsgb_we:
	s_waitcnt lgkmcnt(0)
	s_barrier
	s_add_i32 s19, s8, 1
	s_add_i32 s99, s8, 3
	s_cmp_ge_u32 s99, s4
	s_cbranch_scc1 .LBB0_230
	v_lshl_add_u64 v[92:93], v[34:35], 0, v[0:1]
	v_lshl_add_u64 v[94:95], v[32:33], 0, v[0:1]
	s_cmp_eq_u32 s98, 1
	s_cbranch_scc1 .Lsgb_l1
	s_cmp_eq_u32 s98, 2
	s_cbranch_scc1 .Lsgb_l2
	global_load_dwordx4 v[6:9], v[92:93], off offset:1024
	global_load_dwordx4 v[10:13], v[92:93], off offset:1152
	global_load_dwordx4 v[14:17], v[94:95], off offset:1024
	global_load_dwordx4 v[18:21], v[94:95], off offset:1152
	s_branch .LBB0_230
.Lsgb_l1:
	global_load_dwordx4 v[60:63], v[92:93], off offset:1024
	global_load_dwordx4 v[64:67], v[92:93], off offset:1152
	global_load_dwordx4 v[68:71], v[94:95], off offset:1024
	global_load_dwordx4 v[72:75], v[94:95], off offset:1152
	s_branch .LBB0_230
.Lsgb_l2:
	global_load_dwordx4 v[76:79], v[92:93], off offset:1024
	global_load_dwordx4 v[80:83], v[92:93], off offset:1152
	global_load_dwordx4 v[84:87], v[94:95], off offset:1024
	global_load_dwordx4 v[88:91], v[94:95], off offset:1152
.LBB0_230:
	s_add_i32 s98, s98, 1
	s_cmp_eq_u32 s98, 3
	s_cselect_b32 s98, 0, s98
	s_and_b32 s9, s8, 3
	s_cmp_lg_u32 s9, 0
	s_cselect_b64 s[28:29], -1, 0
	s_or_b64 s[28:29], s[26:27], s[28:29]
	s_and_b64 vcc, exec, s[28:29]
	s_cbranch_vccnz .LBB0_232
	s_lshr_b32 s28, s8, 2
	s_add_i32 s8, s28, -1
	v_mad_i64_i32 v[40:41], s[8:9], s8, v178, v[30:31]
	v_mad_u64_u32 v[46:47], s[8:9], s28, v178, v[30:31]
	global_load_dwordx2 v[38:39], v[40:41], off
	global_load_dwordx2 v[48:49], v[46:47], off
	s_nop 0
	global_load_dwordx2 v[40:41], v[40:41], off offset:128
	s_nop 0
	global_load_dwordx2 v[46:47], v[46:47], off offset:128
	s_mov_b32 s8, 0x358637bd
	s_waitcnt vmcnt(2)
	v_ffbh_u32_e32 v36, v49
	v_min_u32_e32 v36, 32, v36
	v_lshlrev_b64 v[48:49], v36, v[48:49]
	v_min_u32_e32 v48, 1, v48
	v_or_b32_e32 v48, v49, v48
	v_cvt_f32_u32_e32 v48, v48
	v_sub_u32_e32 v36, 32, v36
	v_ldexp_f32 v49, v48, v36
	v_ffbh_u32_e32 v36, v39
	v_min_u32_e32 v36, 32, v36
	v_lshlrev_b64 v[38:39], v36, v[38:39]
	v_min_u32_e32 v38, 1, v38
	v_or_b32_e32 v38, v39, v38
	v_cvt_f32_u32_e32 v38, v38
	v_sub_u32_e32 v36, 32, v36
	v_ldexp_f32 v48, v38, v36
	v_mov_b64_e32 v[38:39], s[8:9]
	v_pk_fma_f32 v[48:49], v[48:49], s[78:79], v[38:39] op_sel_hi:[1,0,0]
	s_nop 0
	v_mul_f32_e32 v36, 0x4b800000, v48
	v_cmp_gt_f32_e64 s[8:9], s90, v48
	v_cmp_gt_f32_e32 vcc, s90, v49
	s_nop 0
	v_cndmask_b32_e64 v36, v48, v36, s[8:9]
	v_rsq_f32_e32 v48, v36
	v_mul_f32_e32 v36, 0x4b800000, v49
	v_cndmask_b32_e32 v36, v49, v36, vcc
	v_rsq_f32_e32 v49, v36
	s_nop 0
	v_pk_mul_f32 v[50:51], v[48:49], s[76:77] op_sel_hi:[1,0]
	s_nop 0
	v_cndmask_b32_e64 v36, v48, v50, s[8:9]
	v_cndmask_b32_e32 v48, v49, v51, vcc
	v_div_scale_f32 v49, s[8:9], v48, v48, v36
	v_rcp_f32_e32 v50, v49
	s_nop 0
	v_fma_f32 v51, -v49, v50, 1.0
	v_fmac_f32_e32 v50, v51, v50
	v_div_scale_f32 v51, vcc, v36, v48, v36
	v_mul_f32_e32 v52, v51, v50
	v_fma_f32 v53, -v49, v52, v51
	v_fmac_f32_e32 v52, v53, v50
	v_fma_f32 v49, -v49, v52, v51
	v_div_fmas_f32 v49, v49, v50, v52
	v_div_fixup_f32 v36, v49, v48, v36
	s_waitcnt vmcnt(0)
	v_ffbh_u32_e32 v48, v47
	v_min_u32_e32 v48, 32, v48
	v_lshlrev_b64 v[46:47], v48, v[46:47]
	v_min_u32_e32 v46, 1, v46
	v_or_b32_e32 v46, v47, v46
	v_cvt_f32_u32_e32 v46, v46
	v_sub_u32_e32 v47, 32, v48
	v_pk_mul_f32 v[24:25], v[24:25], v[36:37] op_sel_hi:[1,0]
	v_pk_mul_f32 v[22:23], v[22:23], v[36:37] op_sel_hi:[1,0]
	v_ldexp_f32 v47, v46, v47
	v_ffbh_u32_e32 v46, v41
	v_min_u32_e32 v46, 32, v46
	v_lshlrev_b64 v[40:41], v46, v[40:41]
	v_min_u32_e32 v40, 1, v40
	v_or_b32_e32 v40, v41, v40
	v_cvt_f32_u32_e32 v40, v40
	v_sub_u32_e32 v41, 32, v46
	v_ldexp_f32 v46, v40, v41
	v_pk_fma_f32 v[38:39], v[46:47], s[78:79], v[38:39] op_sel_hi:[1,0,0]
	s_nop 0
	v_mul_f32_e32 v40, 0x4b800000, v38
	v_cmp_gt_f32_e64 s[8:9], s90, v38
	v_cmp_gt_f32_e32 vcc, s90, v39
	s_nop 0
	v_cndmask_b32_e64 v38, v38, v40, s[8:9]
	v_mul_f32_e32 v40, 0x4b800000, v39
	v_cndmask_b32_e32 v39, v39, v40, vcc
	v_rsq_f32_e32 v38, v38
	v_rsq_f32_e32 v39, v39
	s_nop 0
	v_pk_mul_f32 v[40:41], v[38:39], s[76:77] op_sel_hi:[1,0]
	s_nop 0
	v_cndmask_b32_e64 v38, v38, v40, s[8:9]
	v_cndmask_b32_e32 v39, v39, v41, vcc
	v_div_scale_f32 v40, s[8:9], v39, v39, v38
	v_rcp_f32_e32 v41, v40
	s_nop 0
	v_fma_f32 v46, -v40, v41, 1.0
	v_fmac_f32_e32 v41, v46, v41
	v_div_scale_f32 v46, vcc, v38, v39, v38
	v_mul_f32_e32 v47, v46, v41
	v_fma_f32 v48, -v40, v47, v46
	v_fmac_f32_e32 v47, v48, v41
	v_fma_f32 v40, -v40, v47, v46
	v_div_fmas_f32 v40, v40, v41, v47
	v_div_fixup_f32 v38, v40, v39, v38
	v_pk_mul_f32 v[4:5], v[4:5], v[38:39] op_sel_hi:[1,0]
	v_pk_mul_f32 v[2:3], v[2:3], v[38:39] op_sel_hi:[1,0]
